# v119 plus grid barrier: non-leader workgroups poll the top-level generation word directly, leaders no longer bump the per-XCD word
# baseline (speedup 1.0000x reference)
; __device__ __forceinline__ unsigned xb_ld(unsigned* p)              { return __hip_atomic_load(p, __ATOMIC_RELAXED, __HIP_MEMORY_SCOPE_AGENT); }
; __device__ __forceinline__ unsigned xb_add(unsigned* p, unsigned v) { return __hip_atomic_fetch_add(p, v, __ATOMIC_RELAXED, __HIP_MEMORY_SCOPE_AGENT); }
; #define XB_SPIN(cond, bar) do { unsigned _sp = 0; while (cond) { __builtin_amdgcn_s_sleep(1); \
;     if ((++_sp & 255u) == 0u) { if (xb_ld(&(bar)[XB_TMO])) break; if (_sp > XB_SPIN_CAP) { atomicAdd(&(bar)[XB_TMO], 1u); break; } } } } while (0)
; __device__ __forceinline__ void xcd_barrier(const XcdBarrier& b) {
;     ...
;         const unsigned old = xb_add(&bar[XB_XSUB(b.x)], 1u);
;         const unsigned gen = old / nloc;
;         if (old + 1u == (gen + 1u) * nloc) {
;             __builtin_amdgcn_fence(__ATOMIC_RELEASE, "agent");
;             asm volatile("s_waitcnt vmcnt(0)" ::: "memory");
;             const unsigned og = xb_add(&bar[XB_TOP], 1u);
;             const unsigned tg = og / nx;
;             if (og + 1u == (tg + 1u) * nx) xb_add(&bar[XB_TOPGEN], 1u);
;             else XB_SPIN(xb_ld(&bar[XB_TOPGEN]) == tg, bar);
;             __builtin_amdgcn_fence(__ATOMIC_ACQUIRE, "agent");
;             xb_add(&bar[XB_XGEN(b.x)], 1u);
;             asm volatile("s_waitcnt vmcnt(0)" ::: "memory");
;         } else {
;             XB_SPIN(xb_ld(&bar[XB_XGEN(b.x)]) == gen, bar);
.LBB0_143:
	s_or_b64 exec, exec, s[4:5]
	v_cvt_f32_u32_e32 v5, v3
	s_waitcnt vmcnt(0)
	v_readfirstlane_b32 s2, v4
	v_sub_u32_e32 v4, 0, v3
	v_rcp_iflag_f32_e32 v5, v5
	v_add_u32_e32 v6, s2, v2
	v_mul_f32_e32 v5, 0x4f7ffffe, v5
	v_cvt_u32_f32_e32 v5, v5
	v_mul_lo_u32 v2, v4, v5
	v_mul_hi_u32 v2, v5, v2
	v_add_u32_e32 v2, v5, v2
	v_mul_hi_u32 v2, v6, v2
	v_mul_lo_u32 v4, v2, v3
	v_sub_u32_e32 v4, v6, v4
	v_add_u32_e32 v5, 1, v2
	v_cmp_ge_u32_e32 vcc, v4, v3
	s_nop 1
	v_cndmask_b32_e32 v2, v2, v5, vcc
	v_sub_u32_e32 v5, v4, v3
	v_cndmask_b32_e32 v4, v4, v5, vcc
	v_add_u32_e32 v5, 1, v2
	v_cmp_ge_u32_e32 vcc, v4, v3
	v_add_u32_e32 v4, 1, v6
	s_nop 0
	v_cndmask_b32_e32 v2, v2, v5, vcc
	v_mul_lo_u32 v5, v3, v2
	v_add_u32_e32 v3, v5, v3
	v_cmp_ne_u32_e32 vcc, v4, v3
	s_and_saveexec_b64 s[2:3], vcc
	s_xor_b64 s[2:3], exec, s[2:3]
	s_cbranch_execz .LBB0_157
	v_readlane_b32 s36, v253, 0
	v_readlane_b32 s48, v253, 12
	v_readlane_b32 s49, v253, 13
	s_add_i32 s4, s20, 0x900
	s_mov_b32 s5, 0
	v_readlane_b32 s50, v253, 14
	v_readlane_b32 s51, v253, 15
	s_mov_b64 s[24:25], s[48:49]
	s_lshl_b64 s[4:5], s[4:5], 2
	s_mov_b64 s[26:27], s[50:51]
	s_add_u32 s6, s26, 0x3500
	s_addc_u32 s7, s27, 0
	s_waitcnt lgkmcnt(0)
	v_mov_b32_e32 v1, 0
	global_load_dword v3, v1, s[6:7] sc1
	v_readlane_b32 s37, v253, 1
	v_readlane_b32 s38, v253, 2
	v_readlane_b32 s39, v253, 3
	v_readlane_b32 s40, v253, 4
	v_readlane_b32 s41, v253, 5
	v_readlane_b32 s42, v253, 6
	v_readlane_b32 s43, v253, 7
	v_readlane_b32 s44, v253, 8
	v_readlane_b32 s45, v253, 9
	v_readlane_b32 s46, v253, 10
	v_readlane_b32 s47, v253, 11
	s_waitcnt vmcnt(0)
	v_cmp_eq_u32_e32 vcc, v3, v2
	s_and_saveexec_b64 s[4:5], vcc
	s_cbranch_execz .LBB0_156
	s_mov_b32 s18, 1
	s_mov_b64 s[8:9], 0
	s_branch .LBB0_147

; __device__ __forceinline__ unsigned xb_add(unsigned* p, unsigned v) { return __hip_atomic_fetch_add(p, v, __ATOMIC_RELAXED, __HIP_MEMORY_SCOPE_AGENT); }
; __device__ __forceinline__ void xcd_barrier(const XcdBarrier& b) {
;     ...
;             __builtin_amdgcn_fence(__ATOMIC_ACQUIRE, "agent");
;             xb_add(&bar[XB_XGEN(b.x)], 1u);
;             asm volatile("s_waitcnt vmcnt(0)" ::: "memory");
.LBB0_174:
	s_or_b64 exec, exec, s[2:3]
	s_mov_b64 s[2:3], exec
	v_mbcnt_lo_u32_b32 v1, s2, 0
	v_mbcnt_hi_u32_b32 v1, s3, v1
	s_mov_b32 s7, 0
	v_cmp_eq_u32_e32 vcc, 0, v1
	s_waitcnt vmcnt(0)
	buffer_inv sc1
	s_and_saveexec_b64 s[4:5], vcc
	s_cbranch_execz .LBB0_176
	s_add_i32 s6, s20, 0x900
	v_readlane_b32 s8, v253, 0
	s_lshl_b64 s[6:7], s[6:7], 2
	v_readlane_b32 s22, v253, 14
	v_readlane_b32 s23, v253, 15
	s_add_u32 s6, s22, s6
	s_addc_u32 s7, s23, s7
	s_bcnt1_i32_b64 s2, s[2:3]
	v_mov_b32_e32 v1, 0
	v_mov_b32_e32 v2, s2
	s_nop 0
	v_readlane_b32 s9, v253, 1
	v_readlane_b32 s10, v253, 2
	v_readlane_b32 s11, v253, 3
	v_readlane_b32 s12, v253, 4
	v_readlane_b32 s13, v253, 5
	v_readlane_b32 s14, v253, 6
	v_readlane_b32 s15, v253, 7
	v_readlane_b32 s16, v253, 8
	v_readlane_b32 s17, v253, 9
	v_readlane_b32 s18, v253, 10
	v_readlane_b32 s19, v253, 11
	v_readlane_b32 s20, v253, 12
	v_readlane_b32 s21, v253, 13

; __device__ __forceinline__ unsigned xb_ld(unsigned* p)              { return __hip_atomic_load(p, __ATOMIC_RELAXED, __HIP_MEMORY_SCOPE_AGENT); }
; __device__ __forceinline__ unsigned xb_add(unsigned* p, unsigned v) { return __hip_atomic_fetch_add(p, v, __ATOMIC_RELAXED, __HIP_MEMORY_SCOPE_AGENT); }
; #define XB_SPIN(cond, bar) do { unsigned _sp = 0; while (cond) { __builtin_amdgcn_s_sleep(1); \
;     if ((++_sp & 255u) == 0u) { if (xb_ld(&(bar)[XB_TMO])) break; if (_sp > XB_SPIN_CAP) { atomicAdd(&(bar)[XB_TMO], 1u); break; } } } } while (0)
; __device__ __forceinline__ void xcd_barrier(const XcdBarrier& b) {
;     ...
;         const unsigned old = xb_add(&bar[XB_XSUB(b.x)], 1u);
;         const unsigned gen = old / nloc;
;         if (old + 1u == (gen + 1u) * nloc) {
;             __builtin_amdgcn_fence(__ATOMIC_RELEASE, "agent");
;             asm volatile("s_waitcnt vmcnt(0)" ::: "memory");
;             const unsigned og = xb_add(&bar[XB_TOP], 1u);
;             const unsigned tg = og / nx;
;             if (og + 1u == (tg + 1u) * nx) xb_add(&bar[XB_TOPGEN], 1u);
;             else XB_SPIN(xb_ld(&bar[XB_TOPGEN]) == tg, bar);
;             __builtin_amdgcn_fence(__ATOMIC_ACQUIRE, "agent");
;             xb_add(&bar[XB_XGEN(b.x)], 1u);
;             asm volatile("s_waitcnt vmcnt(0)" ::: "memory");
;         } else {
;             XB_SPIN(xb_ld(&bar[XB_XGEN(b.x)]) == gen, bar);
.LBB0_255:
	s_or_b64 exec, exec, s[6:7]
	v_cvt_f32_u32_e32 v4, v2
	s_waitcnt vmcnt(0)
	v_readfirstlane_b32 s4, v3
	v_sub_u32_e32 v3, 0, v2
	v_rcp_iflag_f32_e32 v4, v4
	v_add_u32_e32 v5, s4, v1
	v_mul_f32_e32 v4, 0x4f7ffffe, v4
	v_cvt_u32_f32_e32 v4, v4
	v_mul_lo_u32 v1, v3, v4
	v_mul_hi_u32 v1, v4, v1
	v_add_u32_e32 v1, v4, v1
	v_mul_hi_u32 v1, v5, v1
	v_mul_lo_u32 v3, v1, v2
	v_sub_u32_e32 v3, v5, v3
	v_add_u32_e32 v4, 1, v1
	v_cmp_ge_u32_e32 vcc, v3, v2
	s_nop 1
	v_cndmask_b32_e32 v1, v1, v4, vcc
	v_sub_u32_e32 v4, v3, v2
	v_cndmask_b32_e32 v3, v3, v4, vcc
	v_add_u32_e32 v4, 1, v1
	v_cmp_ge_u32_e32 vcc, v3, v2
	v_add_u32_e32 v3, 1, v5
	s_nop 0
	v_cndmask_b32_e32 v1, v1, v4, vcc
	v_mul_lo_u32 v4, v2, v1
	v_add_u32_e32 v2, v4, v2
	v_cmp_ne_u32_e32 vcc, v3, v2
	s_and_saveexec_b64 s[4:5], vcc
	s_xor_b64 s[4:5], exec, s[4:5]
	s_cbranch_execz .LBB0_269
	v_readlane_b32 s36, v253, 0
	v_readlane_b32 s48, v253, 12
	v_readlane_b32 s49, v253, 13
	s_add_i32 s72, s21, 0x900
	v_readlane_b32 s50, v253, 14
	v_readlane_b32 s51, v253, 15
	s_mov_b64 s[24:25], s[48:49]
	s_lshl_b64 s[6:7], s[72:73], 2
	s_mov_b64 s[26:27], s[50:51]
	s_add_u32 s8, s26, 0x3500
	s_addc_u32 s9, s27, 0
	s_waitcnt lgkmcnt(0)
	global_load_dword v0, v128, s[8:9] sc1
	v_readlane_b32 s37, v253, 1
	v_readlane_b32 s38, v253, 2
	v_readlane_b32 s39, v253, 3
	v_readlane_b32 s40, v253, 4
	v_readlane_b32 s41, v253, 5
	v_readlane_b32 s42, v253, 6
	v_readlane_b32 s43, v253, 7
	v_readlane_b32 s44, v253, 8
	v_readlane_b32 s45, v253, 9
	v_readlane_b32 s46, v253, 10
	v_readlane_b32 s47, v253, 11
	s_waitcnt vmcnt(0)
	v_cmp_eq_u32_e32 vcc, v0, v1
	s_and_saveexec_b64 s[6:7], vcc
	s_cbranch_execz .LBB0_268
	s_mov_b32 s22, 1
	s_mov_b64 s[10:11], 0
	s_branch .LBB0_259

; __device__ __forceinline__ unsigned xb_add(unsigned* p, unsigned v) { return __hip_atomic_fetch_add(p, v, __ATOMIC_RELAXED, __HIP_MEMORY_SCOPE_AGENT); }
; __device__ __forceinline__ void xcd_barrier(const XcdBarrier& b) {
;     ...
;             __builtin_amdgcn_fence(__ATOMIC_ACQUIRE, "agent");
;             xb_add(&bar[XB_XGEN(b.x)], 1u);
;             asm volatile("s_waitcnt vmcnt(0)" ::: "memory");
.LBB0_286:
	s_or_b64 exec, exec, s[4:5]
	s_mov_b64 s[4:5], exec
	v_mbcnt_lo_u32_b32 v0, s4, 0
	v_mbcnt_hi_u32_b32 v0, s5, v0
	v_cmp_eq_u32_e32 vcc, 0, v0
	s_waitcnt vmcnt(0)
	buffer_inv sc1
	s_and_saveexec_b64 s[6:7], vcc
	s_cbranch_execz .LBB0_288
	v_readlane_b32 s36, v253, 0
	v_readlane_b32 s48, v253, 12
	v_readlane_b32 s49, v253, 13
	s_add_i32 s72, s21, 0x900
	v_readlane_b32 s50, v253, 14
	v_readlane_b32 s51, v253, 15
	s_mov_b64 s[24:25], s[48:49]
	s_lshl_b64 s[8:9], s[72:73], 2
	s_mov_b64 s[26:27], s[50:51]
	s_add_u32 s8, s26, s8
	s_addc_u32 s9, s27, s9
	s_bcnt1_i32_b64 s4, s[4:5]
	v_mov_b32_e32 v0, s4
	s_nop 0
	v_readlane_b32 s37, v253, 1
	v_readlane_b32 s38, v253, 2
	v_readlane_b32 s39, v253, 3
	v_readlane_b32 s40, v253, 4
	v_readlane_b32 s41, v253, 5
	v_readlane_b32 s42, v253, 6
	v_readlane_b32 s43, v253, 7
	v_readlane_b32 s44, v253, 8
	v_readlane_b32 s45, v253, 9
	v_readlane_b32 s46, v253, 10
	v_readlane_b32 s47, v253, 11

; __device__ __forceinline__ unsigned xb_ld(unsigned* p)              { return __hip_atomic_load(p, __ATOMIC_RELAXED, __HIP_MEMORY_SCOPE_AGENT); }
; __device__ __forceinline__ unsigned xb_add(unsigned* p, unsigned v) { return __hip_atomic_fetch_add(p, v, __ATOMIC_RELAXED, __HIP_MEMORY_SCOPE_AGENT); }
; #define XB_SPIN(cond, bar) do { unsigned _sp = 0; while (cond) { __builtin_amdgcn_s_sleep(1); \
;     if ((++_sp & 255u) == 0u) { if (xb_ld(&(bar)[XB_TMO])) break; if (_sp > XB_SPIN_CAP) { atomicAdd(&(bar)[XB_TMO], 1u); break; } } } } while (0)
; __device__ __forceinline__ void xcd_barrier(const XcdBarrier& b) {
;     ...
;         const unsigned old = xb_add(&bar[XB_XSUB(b.x)], 1u);
;         const unsigned gen = old / nloc;
;         if (old + 1u == (gen + 1u) * nloc) {
;             __builtin_amdgcn_fence(__ATOMIC_RELEASE, "agent");
;             asm volatile("s_waitcnt vmcnt(0)" ::: "memory");
;             const unsigned og = xb_add(&bar[XB_TOP], 1u);
;             const unsigned tg = og / nx;
;             if (og + 1u == (tg + 1u) * nx) xb_add(&bar[XB_TOPGEN], 1u);
;             else XB_SPIN(xb_ld(&bar[XB_TOPGEN]) == tg, bar);
;             __builtin_amdgcn_fence(__ATOMIC_ACQUIRE, "agent");
;             xb_add(&bar[XB_XGEN(b.x)], 1u);
;             asm volatile("s_waitcnt vmcnt(0)" ::: "memory");
;         } else {
;             XB_SPIN(xb_ld(&bar[XB_XGEN(b.x)]) == gen, bar);
.LBB0_1629:
	s_or_b64 exec, exec, s[4:5]
	v_cvt_f32_u32_e32 v4, v2
	s_waitcnt vmcnt(0)
	v_readfirstlane_b32 s2, v3
	v_sub_u32_e32 v3, 0, v2
	v_rcp_iflag_f32_e32 v4, v4
	v_add_u32_e32 v5, s2, v1
	v_mul_f32_e32 v4, 0x4f7ffffe, v4
	v_cvt_u32_f32_e32 v4, v4
	v_mul_lo_u32 v1, v3, v4
	v_mul_hi_u32 v1, v4, v1
	v_add_u32_e32 v1, v4, v1
	v_mul_hi_u32 v1, v5, v1
	v_mul_lo_u32 v3, v1, v2
	v_sub_u32_e32 v3, v5, v3
	v_add_u32_e32 v4, 1, v1
	v_cmp_ge_u32_e32 vcc, v3, v2
	s_nop 1
	v_cndmask_b32_e32 v1, v1, v4, vcc
	v_sub_u32_e32 v4, v3, v2
	v_cndmask_b32_e32 v3, v3, v4, vcc
	v_add_u32_e32 v4, 1, v1
	v_cmp_ge_u32_e32 vcc, v3, v2
	v_add_u32_e32 v3, 1, v5
	s_nop 0
	v_cndmask_b32_e32 v1, v1, v4, vcc
	v_mul_lo_u32 v4, v2, v1
	v_add_u32_e32 v2, v4, v2
	v_cmp_ne_u32_e32 vcc, v3, v2
	s_and_saveexec_b64 s[2:3], vcc
	s_xor_b64 s[2:3], exec, s[2:3]
	s_cbranch_execz .LBB0_1643
	v_readlane_b32 s36, v253, 0
	v_readlane_b32 s48, v253, 12
	v_readlane_b32 s49, v253, 13
	s_add_i32 s72, s18, 0x900
	v_readlane_b32 s50, v253, 14
	v_readlane_b32 s51, v253, 15
	s_mov_b64 s[24:25], s[48:49]
	s_lshl_b64 s[4:5], s[72:73], 2
	s_mov_b64 s[26:27], s[50:51]
	s_add_u32 s6, s26, 0x3500
	s_addc_u32 s7, s27, 0
	s_waitcnt lgkmcnt(0)
	global_load_dword v0, v128, s[6:7] sc1
	v_readlane_b32 s37, v253, 1
	v_readlane_b32 s38, v253, 2
	v_readlane_b32 s39, v253, 3
	v_readlane_b32 s40, v253, 4
	v_readlane_b32 s41, v253, 5
	v_readlane_b32 s42, v253, 6
	v_readlane_b32 s43, v253, 7
	v_readlane_b32 s44, v253, 8
	v_readlane_b32 s45, v253, 9
	v_readlane_b32 s46, v253, 10
	v_readlane_b32 s47, v253, 11
	s_waitcnt vmcnt(0)
	v_cmp_eq_u32_e32 vcc, v0, v1
	s_and_saveexec_b64 s[4:5], vcc
	s_cbranch_execz .LBB0_1642
	s_mov_b32 s19, 1
	s_mov_b64 s[8:9], 0
	s_branch .LBB0_1633

; __device__ __forceinline__ unsigned xb_add(unsigned* p, unsigned v) { return __hip_atomic_fetch_add(p, v, __ATOMIC_RELAXED, __HIP_MEMORY_SCOPE_AGENT); }
; __device__ __forceinline__ void xcd_barrier(const XcdBarrier& b) {
;     ...
;             __builtin_amdgcn_fence(__ATOMIC_ACQUIRE, "agent");
;             xb_add(&bar[XB_XGEN(b.x)], 1u);
;             asm volatile("s_waitcnt vmcnt(0)" ::: "memory");
.LBB0_1661:
	s_add_i32 s72, s18, 0x900
	v_readlane_b32 s8, v253, 0
	s_lshl_b64 s[6:7], s[72:73], 2
	v_readlane_b32 s22, v253, 14
	v_readlane_b32 s23, v253, 15
	s_add_u32 s6, s22, s6
	s_addc_u32 s7, s23, s7
	s_bcnt1_i32_b64 s2, s[2:3]
	v_mov_b32_e32 v0, s2
	s_nop 0
	v_readlane_b32 s9, v253, 1
	v_readlane_b32 s10, v253, 2
	v_readlane_b32 s11, v253, 3
	v_readlane_b32 s12, v253, 4
	v_readlane_b32 s13, v253, 5
	v_readlane_b32 s14, v253, 6
	v_readlane_b32 s15, v253, 7
	v_readlane_b32 s16, v253, 8
	v_readlane_b32 s17, v253, 9
	v_readlane_b32 s18, v253, 10
	v_readlane_b32 s19, v253, 11
	v_readlane_b32 s20, v253, 12
	v_readlane_b32 s21, v253, 13
	s_getpc_b64 s[98:99]
